# speedup vs baseline: 1.0087x; 1.0087x over previous
; __device__ __forceinline__ void stg16f(void* p, float a, float b, float c, float d) { typedef float f32x4_ __attribute__((ext_vector_type(4))); const f32x4_ v = {a, b, c, d}; *(__attribute__((address_space(1))) f32x4_*)(p) = v; }
; __device__ __forceinline__ float4 ldg16f(const void* p) { typedef float f32x4_ __attribute__((ext_vector_type(4))); const f32x4_ v = *(const __attribute__((address_space(1))) f32x4_*)(p); return make_float4(v.x, v.y, v.z, v.w); }
; #define EPI_LOOP(...) _Pragma("unroll") for (int ai = 0; ai < 2; ++ai) _Pragma("unroll") for (int bj = 0; bj < 2; ++bj) \
;     _Pragma("unroll") for (int m = 0; m < 4; ++m) _Pragma("unroll") for (int n = 0; n < 2; ++n) { \
;       const int o = toff + (ai * HALF + m * 16) * ld + bj * HALF + n * 16; const f32x4 v = acc[ai][bj][m][n]; __VA_ARGS__ }
; template <class EPIF>
; __device__ __forceinline__ void gemm_stream(const u16* __restrict__ A, const u16* __restrict__ Bt, const int K, const int nM,
;                                             const int nN, const int loc, const int G, EPIF epif, u16* shm, const int wv) {
;     ...
;         float* d = (float*)ep.dst + (long)brow * ld + ccol;
;         const float* r = ep.res + (long)brow * ld + ccol;
;         EPI_LOOP({ const float4 rv = ldg16f(r + o); stg16f(d + o, rv.x + v[0], rv.y + v[1], rv.z + v[2], rv.w + v[3]); })
.LBB0_293:
	s_lshl_b64 s[8:9], s[24:25], 2
	s_lshl_b64 s[10:11], s[22:23], 2
	s_waitcnt lgkmcnt(0)
	v_lshl_add_u64 v[152:153], v[134:135], 0, s[8:9]
	v_lshl_add_u64 v[150:151], v[146:147], 0, s[8:9]
	v_lshl_add_u64 v[152:153], v[152:153], 0, s[10:11]
	v_lshl_add_u64 v[150:151], v[150:151], 0, s[10:11]
	s_lshl_b32 s8, s83, 4
	s_lshl_b32 s9, s83, 7
	s_mov_b32 s10, 0
	v_add_u32_e32 v182, s10, v148
	v_ashrrev_i32_e32 v183, 31, v182
	v_lshlrev_b64 v[182:183], 2, v[182:183]
	v_lshl_add_u64 v[174:175], v[152:153], 0, v[182:183]
	global_load_dwordx4 v[186:189], v[174:175], off
	global_load_dwordx4 v[190:193], v[174:175], off offset:64
	global_load_dwordx4 v[194:197], v[174:175], off offset:512
	global_load_dwordx4 v[198:201], v[174:175], off offset:576
	s_mul_i32 s10, s8, 1
	v_add_u32_e32 v182, s10, v148
	v_ashrrev_i32_e32 v183, 31, v182
	v_lshlrev_b64 v[182:183], 2, v[182:183]
	v_lshl_add_u64 v[174:175], v[152:153], 0, v[182:183]
	global_load_dwordx4 v[202:205], v[174:175], off
	global_load_dwordx4 v[206:209], v[174:175], off offset:64
	global_load_dwordx4 v[216:219], v[174:175], off offset:512
	global_load_dwordx4 v[220:223], v[174:175], off offset:576
	s_mov_b32 s10, 0
	v_add_u32_e32 v182, s10, v148
	v_ashrrev_i32_e32 v183, 31, v182
	v_lshlrev_b64 v[182:183], 2, v[182:183]
	v_lshl_add_u64 v[176:177], v[150:151], 0, v[182:183]
	s_mul_i32 s10, s8, 2
	v_add_u32_e32 v182, s10, v148
	v_ashrrev_i32_e32 v183, 31, v182
	v_lshlrev_b64 v[182:183], 2, v[182:183]
	v_lshl_add_u64 v[174:175], v[152:153], 0, v[182:183]
	s_waitcnt vmcnt(7)
	v_pk_add_f32 v[186:187], v[124:125], v[186:187]
	v_pk_add_f32 v[188:189], v[126:127], v[188:189]
	global_store_dwordx4 v[176:177], v[186:189], off
	global_load_dwordx4 v[186:189], v[174:175], off
	s_waitcnt vmcnt(8)
	v_pk_add_f32 v[190:191], v[120:121], v[190:191]
	v_pk_add_f32 v[192:193], v[122:123], v[192:193]
	global_store_dwordx4 v[176:177], v[190:193], off offset:64
	global_load_dwordx4 v[190:193], v[174:175], off offset:64
	s_waitcnt vmcnt(9)
	v_pk_add_f32 v[194:195], v[108:109], v[194:195]
	v_pk_add_f32 v[196:197], v[110:111], v[196:197]
	global_store_dwordx4 v[176:177], v[194:197], off offset:512
	global_load_dwordx4 v[194:197], v[174:175], off offset:512
	s_waitcnt vmcnt(10)
	v_pk_add_f32 v[198:199], v[104:105], v[198:199]
	v_pk_add_f32 v[200:201], v[106:107], v[200:201]
	global_store_dwordx4 v[176:177], v[198:201], off offset:576
	global_load_dwordx4 v[198:201], v[174:175], off offset:576
	s_mul_i32 s10, s8, 1
	v_add_u32_e32 v182, s10, v148
	v_ashrrev_i32_e32 v183, 31, v182
	v_lshlrev_b64 v[182:183], 2, v[182:183]
	v_lshl_add_u64 v[176:177], v[150:151], 0, v[182:183]
	s_mul_i32 s10, s8, 3
	v_add_u32_e32 v182, s10, v148
	v_ashrrev_i32_e32 v183, 31, v182
	v_lshlrev_b64 v[182:183], 2, v[182:183]
	v_lshl_add_u64 v[174:175], v[152:153], 0, v[182:183]
	s_waitcnt vmcnt(11)
	v_pk_add_f32 v[202:203], v[116:117], v[202:203]
	v_pk_add_f32 v[204:205], v[118:119], v[204:205]
	global_store_dwordx4 v[176:177], v[202:205], off
	global_load_dwordx4 v[202:205], v[174:175], off
	s_waitcnt vmcnt(12)
	v_pk_add_f32 v[206:207], v[112:113], v[206:207]
	v_pk_add_f32 v[208:209], v[114:115], v[208:209]
	global_store_dwordx4 v[176:177], v[206:209], off offset:64
	global_load_dwordx4 v[206:209], v[174:175], off offset:64
	s_waitcnt vmcnt(13)
	v_pk_add_f32 v[216:217], v[92:93], v[216:217]
	v_pk_add_f32 v[218:219], v[94:95], v[218:219]
	global_store_dwordx4 v[176:177], v[216:219], off offset:512
	global_load_dwordx4 v[216:219], v[174:175], off offset:512
	s_waitcnt vmcnt(14)
	v_pk_add_f32 v[220:221], v[88:89], v[220:221]
	v_pk_add_f32 v[222:223], v[90:91], v[222:223]
	global_store_dwordx4 v[176:177], v[220:223], off offset:576
	global_load_dwordx4 v[220:223], v[174:175], off offset:576
	s_mul_i32 s10, s8, 2
	v_add_u32_e32 v182, s10, v148
	v_ashrrev_i32_e32 v183, 31, v182
	v_lshlrev_b64 v[182:183], 2, v[182:183]
	v_lshl_add_u64 v[176:177], v[150:151], 0, v[182:183]
	s_mov_b32 s10, 0
	s_add_i32 s10, s10, s9
	v_add_u32_e32 v182, s10, v148
	v_ashrrev_i32_e32 v183, 31, v182
	v_lshlrev_b64 v[182:183], 2, v[182:183]
	v_lshl_add_u64 v[174:175], v[152:153], 0, v[182:183]
	s_waitcnt vmcnt(14)
	v_pk_add_f32 v[186:187], v[100:101], v[186:187]
	v_pk_add_f32 v[188:189], v[102:103], v[188:189]
	global_store_dwordx4 v[176:177], v[186:189], off
	global_load_dwordx4 v[186:189], v[174:175], off
	s_waitcnt vmcnt(14)
	v_pk_add_f32 v[190:191], v[96:97], v[190:191]
	v_pk_add_f32 v[192:193], v[98:99], v[192:193]
	global_store_dwordx4 v[176:177], v[190:193], off offset:64
	global_load_dwordx4 v[190:193], v[174:175], off offset:64
	s_waitcnt vmcnt(14)
	v_pk_add_f32 v[194:195], v[72:73], v[194:195]
	v_pk_add_f32 v[196:197], v[74:75], v[196:197]
	global_store_dwordx4 v[176:177], v[194:197], off offset:512
	global_load_dwordx4 v[194:197], v[174:175], off offset:512
	s_waitcnt vmcnt(14)
	v_pk_add_f32 v[198:199], v[64:65], v[198:199]
	v_pk_add_f32 v[200:201], v[66:67], v[200:201]
	global_store_dwordx4 v[176:177], v[198:201], off offset:576
	global_load_dwordx4 v[198:201], v[174:175], off offset:576
	s_mul_i32 s10, s8, 3
	v_add_u32_e32 v182, s10, v148
	v_ashrrev_i32_e32 v183, 31, v182
	v_lshlrev_b64 v[182:183], 2, v[182:183]
	v_lshl_add_u64 v[176:177], v[150:151], 0, v[182:183]
	s_mul_i32 s10, s8, 1
	s_add_i32 s10, s10, s9
	v_add_u32_e32 v182, s10, v148
	v_ashrrev_i32_e32 v183, 31, v182
	v_lshlrev_b64 v[182:183], 2, v[182:183]
	v_lshl_add_u64 v[174:175], v[152:153], 0, v[182:183]
	s_waitcnt vmcnt(14)
; __device__ __forceinline__ void stg16f(void* p, float a, float b, float c, float d) { typedef float f32x4_ __attribute__((ext_vector_type(4))); const f32x4_ v = {a, b, c, d}; *(__attribute__((address_space(1))) f32x4_*)(p) = v; }
; __device__ __forceinline__ float4 ldg16f(const void* p) { typedef float f32x4_ __attribute__((ext_vector_type(4))); const f32x4_ v = *(const __attribute__((address_space(1))) f32x4_*)(p); return make_float4(v.x, v.y, v.z, v.w); }
; #define EPI_LOOP(...) _Pragma("unroll") for (int ai = 0; ai < 2; ++ai) _Pragma("unroll") for (int bj = 0; bj < 2; ++bj) \
;     _Pragma("unroll") for (int m = 0; m < 4; ++m) _Pragma("unroll") for (int n = 0; n < 2; ++n) { \
;       const int o = toff + (ai * HALF + m * 16) * ld + bj * HALF + n * 16; const f32x4 v = acc[ai][bj][m][n]; __VA_ARGS__ }
; template <class EPIF>
; __device__ __forceinline__ void gemm_stream(const u16* __restrict__ A, const u16* __restrict__ Bt, const int K, const int nM,
;                                             const int nN, const int loc, const int G, EPIF epif, u16* shm, const int wv) {
;     ...
;         float* d = (float*)ep.dst + (long)brow * ld + ccol;
;         const float* r = ep.res + (long)brow * ld + ccol;
;         EPI_LOOP({ const float4 rv = ldg16f(r + o); stg16f(d + o, rv.x + v[0], rv.y + v[1], rv.z + v[2], rv.w + v[3]); })
	v_pk_add_f32 v[202:203], v[84:85], v[202:203]
	v_pk_add_f32 v[204:205], v[86:87], v[204:205]
	global_store_dwordx4 v[176:177], v[202:205], off
	global_load_dwordx4 v[202:205], v[174:175], off
	s_waitcnt vmcnt(14)
	v_pk_add_f32 v[206:207], v[80:81], v[206:207]
	v_pk_add_f32 v[208:209], v[82:83], v[208:209]
	global_store_dwordx4 v[176:177], v[206:209], off offset:64
	global_load_dwordx4 v[206:209], v[174:175], off offset:64
	s_waitcnt vmcnt(14)
	v_pk_add_f32 v[216:217], v[56:57], v[216:217]
	v_pk_add_f32 v[218:219], v[58:59], v[218:219]
	global_store_dwordx4 v[176:177], v[216:219], off offset:512
	global_load_dwordx4 v[216:219], v[174:175], off offset:512
	s_waitcnt vmcnt(14)
	v_pk_add_f32 v[220:221], v[48:49], v[220:221]
	v_pk_add_f32 v[222:223], v[50:51], v[222:223]
	global_store_dwordx4 v[176:177], v[220:223], off offset:576
	global_load_dwordx4 v[220:223], v[174:175], off offset:576
	s_mov_b32 s10, 0
	s_add_i32 s10, s10, s9
	v_add_u32_e32 v182, s10, v148
	v_ashrrev_i32_e32 v183, 31, v182
	v_lshlrev_b64 v[182:183], 2, v[182:183]
	v_lshl_add_u64 v[176:177], v[150:151], 0, v[182:183]
	s_mul_i32 s10, s8, 2
	s_add_i32 s10, s10, s9
	v_add_u32_e32 v182, s10, v148
	v_ashrrev_i32_e32 v183, 31, v182
	v_lshlrev_b64 v[182:183], 2, v[182:183]
	v_lshl_add_u64 v[174:175], v[152:153], 0, v[182:183]
	s_waitcnt vmcnt(14)
	v_pk_add_f32 v[186:187], v[76:77], v[186:187]
	v_pk_add_f32 v[188:189], v[78:79], v[188:189]
	global_store_dwordx4 v[176:177], v[186:189], off
	global_load_dwordx4 v[186:189], v[174:175], off
	s_waitcnt vmcnt(14)
	v_pk_add_f32 v[190:191], v[68:69], v[190:191]
	v_pk_add_f32 v[192:193], v[70:71], v[192:193]
	global_store_dwordx4 v[176:177], v[190:193], off offset:64
	global_load_dwordx4 v[190:193], v[174:175], off offset:64
	s_waitcnt vmcnt(14)
	v_pk_add_f32 v[194:195], v[36:37], v[194:195]
	v_pk_add_f32 v[196:197], v[38:39], v[196:197]
	global_store_dwordx4 v[176:177], v[194:197], off offset:512
	global_load_dwordx4 v[194:197], v[174:175], off offset:512
	s_waitcnt vmcnt(14)
	v_pk_add_f32 v[198:199], v[32:33], v[198:199]
	v_pk_add_f32 v[200:201], v[34:35], v[200:201]
	global_store_dwordx4 v[176:177], v[198:201], off offset:576
	global_load_dwordx4 v[198:201], v[174:175], off offset:576
	s_mul_i32 s10, s8, 1
	s_add_i32 s10, s10, s9
	v_add_u32_e32 v182, s10, v148
	v_ashrrev_i32_e32 v183, 31, v182
	v_lshlrev_b64 v[182:183], 2, v[182:183]
	v_lshl_add_u64 v[176:177], v[150:151], 0, v[182:183]
	s_mul_i32 s10, s8, 3
	s_add_i32 s10, s10, s9
	v_add_u32_e32 v182, s10, v148
	v_ashrrev_i32_e32 v183, 31, v182
	v_lshlrev_b64 v[182:183], 2, v[182:183]
	v_lshl_add_u64 v[174:175], v[152:153], 0, v[182:183]
	s_waitcnt vmcnt(14)
	v_pk_add_f32 v[202:203], v[60:61], v[202:203]
	v_pk_add_f32 v[204:205], v[62:63], v[204:205]
	global_store_dwordx4 v[176:177], v[202:205], off
	global_load_dwordx4 v[202:205], v[174:175], off
	s_waitcnt vmcnt(14)
	v_pk_add_f32 v[206:207], v[52:53], v[206:207]
	v_pk_add_f32 v[208:209], v[54:55], v[208:209]
	global_store_dwordx4 v[176:177], v[206:209], off offset:64
	global_load_dwordx4 v[206:209], v[174:175], off offset:64
	s_waitcnt vmcnt(14)
	v_pk_add_f32 v[216:217], v[20:21], v[216:217]
	v_pk_add_f32 v[218:219], v[22:23], v[218:219]
	global_store_dwordx4 v[176:177], v[216:219], off offset:512
	global_load_dwordx4 v[216:219], v[174:175], off offset:512
	s_waitcnt vmcnt(14)
	v_pk_add_f32 v[220:221], v[16:17], v[220:221]
	v_pk_add_f32 v[222:223], v[18:19], v[222:223]
	global_store_dwordx4 v[176:177], v[220:223], off offset:576
	global_load_dwordx4 v[220:223], v[174:175], off offset:576
	s_mul_i32 s10, s8, 2
	s_add_i32 s10, s10, s9
	v_add_u32_e32 v182, s10, v148
	v_ashrrev_i32_e32 v183, 31, v182
	v_lshlrev_b64 v[182:183], 2, v[182:183]
	v_lshl_add_u64 v[176:177], v[150:151], 0, v[182:183]
	s_waitcnt vmcnt(14)
	v_pk_add_f32 v[186:187], v[44:45], v[186:187]
	v_pk_add_f32 v[188:189], v[46:47], v[188:189]
	global_store_dwordx4 v[176:177], v[186:189], off
	s_waitcnt vmcnt(13)
	v_pk_add_f32 v[190:191], v[40:41], v[190:191]
	v_pk_add_f32 v[192:193], v[42:43], v[192:193]
	global_store_dwordx4 v[176:177], v[190:193], off offset:64
	s_waitcnt vmcnt(12)
	v_pk_add_f32 v[194:195], v[12:13], v[194:195]
	v_pk_add_f32 v[196:197], v[14:15], v[196:197]
	global_store_dwordx4 v[176:177], v[194:197], off offset:512
	s_waitcnt vmcnt(11)
	v_pk_add_f32 v[198:199], v[8:9], v[198:199]
	v_pk_add_f32 v[200:201], v[10:11], v[200:201]
	global_store_dwordx4 v[176:177], v[198:201], off offset:576
	s_mul_i32 s10, s8, 3
	s_add_i32 s10, s10, s9
	v_add_u32_e32 v182, s10, v148
	v_ashrrev_i32_e32 v183, 31, v182
	v_lshlrev_b64 v[182:183], 2, v[182:183]
	v_lshl_add_u64 v[176:177], v[150:151], 0, v[182:183]
	s_waitcnt vmcnt(10)
	v_pk_add_f32 v[202:203], v[28:29], v[202:203]
	v_pk_add_f32 v[204:205], v[30:31], v[204:205]
	global_store_dwordx4 v[176:177], v[202:205], off
	s_waitcnt vmcnt(9)
	v_pk_add_f32 v[206:207], v[24:25], v[206:207]
	v_pk_add_f32 v[208:209], v[26:27], v[208:209]
	global_store_dwordx4 v[176:177], v[206:209], off offset:64
	s_waitcnt vmcnt(8)
	v_pk_add_f32 v[216:217], v[4:5], v[216:217]
	v_pk_add_f32 v[218:219], v[6:7], v[218:219]
	global_store_dwordx4 v[176:177], v[216:219], off offset:512
	s_waitcnt vmcnt(7)
	v_pk_add_f32 v[220:221], v[0:1], v[220:221]
	v_pk_add_f32 v[222:223], v[2:3], v[222:223]
	global_store_dwordx4 v[176:177], v[220:223], off offset:576
	s_cbranch_execnz .LBB0_185
